# GDN staging waves branch around the per-block register zeroing ladder (16 counted waits + 16 moves) that only the compute waves need
# speedup vs baseline: 1.0881x; 1.0048x over previous
.LBB0_964:
	s_and_b64 vcc, exec, s[38:39]
	s_cbranch_vccz .LBB0_966
	s_and_b64 s[4:5], s[42:43], s[46:47]
	s_waitcnt vmcnt(15)
	v_mov_b32_e32 v139, 0
	s_andn2_b64 vcc, exec, s[4:5]
	s_waitcnt vmcnt(14)
	v_mov_b32_e32 v140, 0
	s_waitcnt vmcnt(13)
	v_mov_b32_e32 v141, 0
	s_waitcnt vmcnt(12)
	v_mov_b32_e32 v143, 0
	s_waitcnt vmcnt(11)
	v_mov_b32_e32 v144, 0
	s_waitcnt vmcnt(10)
	v_mov_b32_e32 v145, 0
	s_waitcnt vmcnt(9)
	v_mov_b32_e32 v146, 0
	s_waitcnt vmcnt(8)
	v_mov_b32_e32 v147, 0
	s_waitcnt vmcnt(7)
	v_mov_b32_e32 v148, 0
	s_waitcnt vmcnt(6)
	v_mov_b32_e32 v150, 0
	s_waitcnt vmcnt(5)
	v_mov_b32_e32 v151, 0
	s_waitcnt vmcnt(4)
	v_mov_b32_e32 v152, 0
	s_waitcnt vmcnt(3)
	v_mov_b32_e32 v153, 0
	s_waitcnt vmcnt(2)
	v_mov_b32_e32 v154, 0
	s_waitcnt vmcnt(1)
	v_mov_b32_e32 v155, 0
	s_waitcnt vmcnt(0)
	v_mov_b32_e32 v149, 0
	s_cbranch_vccnz .LBB0_966
	s_add_i32 s4, s48, s56
	s_ashr_i32 s5, s4, 31
	v_readlane_b32 s64, v252, 4
	s_lshl_b64 s[4:5], s[4:5], 18
	v_readlane_b32 s72, v252, 12
	v_readlane_b32 s73, v252, 13
	s_add_u32 s4, s72, s4
	s_addc_u32 s5, s73, s5
	s_lshl_b32 s48, s49, 16
	s_add_u32 s4, s4, s48
	s_addc_u32 s5, s5, 0
	s_lshl_b32 s48, s63, 6
	s_add_u32 s4, s4, s48
	s_addc_u32 s5, s5, 0
	s_lshl_b32 s48, s59, 2
	s_add_u32 s4, s4, s48
	s_addc_u32 s5, s5, 0
	v_lshlrev_b32_e32 v2, 2, v161
	v_lshl_add_u64 v[0:1], s[4:5], 0, v[2:3]
	v_lshlrev_b32_e32 v2, 13, v156
	v_lshl_add_u64 v[0:1], v[0:1], 0, v[2:3]
	global_load_dword v139, v[0:1], off
	global_load_dword v140, v[0:1], off offset:512
	global_load_dword v141, v[0:1], off offset:1024
	global_load_dword v143, v[0:1], off offset:1536
	global_load_dword v144, v[0:1], off offset:2048
	global_load_dword v145, v[0:1], off offset:2560
	global_load_dword v146, v[0:1], off offset:3072
	global_load_dword v147, v[0:1], off offset:3584
	v_add_co_u32_e32 v0, vcc, 0x1000, v0
	v_readlane_b32 s65, v252, 5
	s_nop 0
	v_addc_co_u32_e32 v1, vcc, 0, v1, vcc
	global_load_dword v148, v[0:1], off
	global_load_dword v150, v[0:1], off offset:512
	global_load_dword v151, v[0:1], off offset:1024
	global_load_dword v152, v[0:1], off offset:1536
	global_load_dword v153, v[0:1], off offset:2048
	global_load_dword v154, v[0:1], off offset:2560
	global_load_dword v155, v[0:1], off offset:3072
	global_load_dword v149, v[0:1], off offset:3584
	v_readlane_b32 s66, v252, 6
	v_readlane_b32 s67, v252, 7
	v_readlane_b32 s68, v252, 8
	v_readlane_b32 s69, v252, 9
	v_readlane_b32 s70, v252, 10
	v_readlane_b32 s71, v252, 11
	v_readlane_b32 s74, v252, 14
	v_readlane_b32 s75, v252, 15
	v_readlane_b32 s76, v252, 16
	v_readlane_b32 s77, v252, 17
	v_readlane_b32 s78, v252, 18
	v_readlane_b32 s79, v252, 19
